# GEMM K-loops: loop-control scalar ops hoisted above the per-iteration barrier so only the branch follows it
# baseline (speedup 1.0000x reference)
; #define PG8_STAGE(bufoff, gbase, voff) do { _Pragma("unroll") for (int _i = 0; _i < 2; ++_i) \
;         __builtin_amdgcn_global_load_lds((const unsigned*)((const char*)(gbase) + (voff)[_i]), (PG8_LAS unsigned*)(lds + (bufoff) + ldsw + _i * 8192), 16, 0, 0); } while (0)
; #define PG8_LDA(dst, b, h) do { _Pragma("unroll") for (int m = 0; m < 4; ++m) _Pragma("unroll") for (int k = 0; k < 2; ++k) dst[m][k] = *(const PG8_LAS bf16x8*)(lds + PG8_SA(b, h) + aoff + m * 2048 + k * 1024); } while (0)
; #define PG8_LDB(dst, b, h) do { _Pragma("unroll") for (int n = 0; n < 2; ++n) _Pragma("unroll") for (int k = 0; k < 2; ++k) dst[n][k] = *(const PG8_LAS bf16x8*)(lds + PG8_SB(b, h) + boff + n * 2048 + k * 1024); } while (0)
; #define PG8_MMA(ai, bj, At, Bt) do { __builtin_amdgcn_s_setprio(1); _Pragma("unroll") for (int m = 0; m < 4; ++m) _Pragma("unroll") for (int n = 0; n < 2; ++n) _Pragma("unroll") for (int k = 0; k < 2; ++k) \
;         acc[ai][bj][m][n] = __builtin_amdgcn_mfma_f32_16x16x32_bf16(Bt[n][k], At[m][k], acc[ai][bj][m][n], 0, 0, 0); __builtin_amdgcn_s_setprio(0); } while (0)
; #define PG8_WAIT_V(n) asm volatile("s_waitcnt vmcnt(" #n ")" ::: "memory")
; #define PG8_WAIT_L(n) asm volatile("s_waitcnt lgkmcnt(" #n ")" ::: "memory")
; #define PG8_BAR __builtin_amdgcn_s_barrier()
; #define PG8_SCHED __builtin_amdgcn_sched_barrier(0)
; #define PG8_STAGE(bufoff, gbase, voff) do { _Pragma("unroll") for (int _i = 0; _i < 2; ++_i) \
;         __builtin_amdgcn_global_load_lds((const unsigned*)((const char*)(gbase) + (voff)[_i]), (PG8_LAS unsigned*)(lds + (bufoff) + ldsw + _i * 8192), 16, 0, 0); } while (0)
; #define PG8_BAR __builtin_amdgcn_s_barrier()
; template <class Epi, class Sched, bool ALIGN_EPI = false, bool SP2 = false>
; __device__ __forceinline__ void gemm_phase(PG8_LAS unsigned char* lds, const Gemm g, const Sched& S, const Epi& E, const int tid_in) {
;     ...
;             PG8_LDB(B0, 0, 0); PG8_LDB(B1, 0, 1); PG8_SCHED; PG8_LDA(At, 0, 0); PG8_STAGE(PG8_SA(1, 1), a1 + hstep, voffA);
;             PG8_WAIT_V(8); PG8_WAIT_L(0); PG8_BAR; PG8_MMA(0, 0, At, B0); PG8_MMA(0, 1, At, B1); PG8_BAR; PG8_SCHED;
;             PG8_LDA(At, 0, 1); PG8_STAGE(PG8_SB(0, 0), b2, voffB); PG8_STAGE(PG8_SB(0, 1), b2 + hstep, voffB); PG8_STAGE(PG8_SA(0, 0), a2, voffA);
;             PG8_WAIT_V(8); PG8_WAIT_L(0); PG8_BAR; PG8_MMA(1, 0, At, B0); PG8_MMA(1, 1, At, B1); PG8_BAR; PG8_SCHED;
.LBB0_31:
	s_add_u32 s51, s64, s90
	s_addc_u32 s52, s65, s91
	s_add_u32 s51, s51, 0x100
	s_addc_u32 s52, s52, 0
	s_add_u32 s94, s57, s90
	s_addc_u32 s53, s68, s91
	s_add_i32 s95, 0, 0x10000
	s_cmpk_eq_i32 s90, 0x700
	s_cselect_b32 s55, s69, s52
	s_cselect_b32 s54, s71, s51
	v_add_u32_e32 v146, s95, v144
	s_cselect_b32 s53, s67, s53
	s_cselect_b32 s52, s80, s94
	s_add_i32 s51, 0, 0x14000
	ds_read_b128 v[150:153], v146
	ds_read_b128 v[154:157], v146 offset:1024
	ds_read_b128 v[172:175], v146 offset:2048
	ds_read_b128 v[176:179], v146 offset:3072
	v_add_u32_e32 v146, s51, v144
	ds_read_b128 v[180:183], v146
	ds_read_b128 v[184:187], v146 offset:1024
	ds_read_b128 v[188:191], v146 offset:2048
	ds_read_b128 v[202:205], v146 offset:3072
	v_lshl_add_u64 v[146:147], v[140:141], 0, s[90:91]
	s_add_i32 m0, s40, 0xc000
	ds_read_b128 v[206:209], v145
	ds_read_b128 v[210:213], v145 offset:1024
	ds_read_b128 v[214:217], v145 offset:2048
	ds_read_b128 v[218:221], v145 offset:3072
	ds_read_b128 v[222:225], v145 offset:4096
	ds_read_b128 v[226:229], v145 offset:5120
	ds_read_b128 v[230:233], v145 offset:6144
	ds_read_b128 v[234:237], v145 offset:7168
	global_load_lds_dwordx4 v[146:147], off
	v_lshl_add_u64 v[146:147], v[142:143], 0, s[90:91]
	s_add_i32 m0, s40, 0xe000
	s_nop 0
	global_load_lds_dwordx4 v[146:147], off
	s_waitcnt vmcnt(8)
	s_waitcnt lgkmcnt(0)
	s_barrier
	s_setprio 1
	s_waitcnt lgkmcnt(0)
	v_mfma_f32_16x16x32_bf16 v[126:129], v[150:153], v[206:209], v[126:129]
	v_mfma_f32_16x16x32_bf16 v[122:125], v[172:175], v[206:209], v[122:125]
	v_mfma_f32_16x16x32_bf16 v[110:113], v[150:153], v[214:217], v[110:113]
	v_mfma_f32_16x16x32_bf16 v[106:109], v[172:175], v[214:217], v[106:109]
	v_mfma_f32_16x16x32_bf16 v[94:97], v[150:153], v[222:225], v[94:97]
	v_mfma_f32_16x16x32_bf16 v[90:93], v[172:175], v[222:225], v[90:93]
	v_mfma_f32_16x16x32_bf16 v[78:81], v[150:153], v[230:233], v[78:81]
	v_mfma_f32_16x16x32_bf16 v[74:77], v[172:175], v[230:233], v[74:77]
	v_mfma_f32_16x16x32_bf16 v[126:129], v[154:157], v[210:213], v[126:129]
	v_mfma_f32_16x16x32_bf16 v[122:125], v[176:179], v[210:213], v[122:125]
	v_mfma_f32_16x16x32_bf16 v[110:113], v[154:157], v[218:221], v[110:113]
	v_mfma_f32_16x16x32_bf16 v[106:109], v[176:179], v[218:221], v[106:109]
	v_mfma_f32_16x16x32_bf16 v[94:97], v[154:157], v[226:229], v[94:97]
	v_mfma_f32_16x16x32_bf16 v[90:93], v[176:179], v[226:229], v[90:93]
	v_mfma_f32_16x16x32_bf16 v[78:81], v[154:157], v[234:237], v[78:81]
	v_mfma_f32_16x16x32_bf16 v[74:77], v[176:179], v[234:237], v[74:77]
	s_setprio 0
	s_setprio 1
	v_mfma_f32_16x16x32_bf16 v[118:121], v[180:183], v[206:209], v[118:121]
	v_mfma_f32_16x16x32_bf16 v[114:117], v[188:191], v[206:209], v[114:117]
	v_mfma_f32_16x16x32_bf16 v[102:105], v[180:183], v[214:217], v[102:105]
	v_mfma_f32_16x16x32_bf16 v[98:101], v[188:191], v[214:217], v[98:101]
	v_mfma_f32_16x16x32_bf16 v[86:89], v[180:183], v[222:225], v[86:89]
	v_mfma_f32_16x16x32_bf16 v[82:85], v[188:191], v[222:225], v[82:85]
	v_mfma_f32_16x16x32_bf16 v[70:73], v[180:183], v[230:233], v[70:73]
	v_mfma_f32_16x16x32_bf16 v[66:69], v[188:191], v[230:233], v[66:69]
	v_mfma_f32_16x16x32_bf16 v[118:121], v[184:187], v[210:213], v[118:121]
	v_mfma_f32_16x16x32_bf16 v[114:117], v[202:205], v[210:213], v[114:117]
	v_mfma_f32_16x16x32_bf16 v[102:105], v[184:187], v[218:221], v[102:105]
	v_mfma_f32_16x16x32_bf16 v[98:101], v[202:205], v[218:221], v[98:101]
	v_mfma_f32_16x16x32_bf16 v[86:89], v[184:187], v[226:229], v[86:89]
	v_mfma_f32_16x16x32_bf16 v[82:85], v[202:205], v[226:229], v[82:85]
	v_mfma_f32_16x16x32_bf16 v[70:73], v[184:187], v[234:237], v[70:73]
	v_mfma_f32_16x16x32_bf16 v[66:69], v[202:205], v[234:237], v[66:69]
	s_setprio 0
	s_barrier
	s_add_i32 s94, s95, s39
	v_lshl_add_u64 v[146:147], s[52:53], 0, v[0:1]
	s_mov_b32 m0, s94
	ds_read_b128 v[206:209], v145 offset:16384
	ds_read_b128 v[210:213], v145 offset:17408
	ds_read_b128 v[214:217], v145 offset:18432
	ds_read_b128 v[218:221], v145 offset:19456
	ds_read_b128 v[222:225], v145 offset:20480
	ds_read_b128 v[226:229], v145 offset:21504
	ds_read_b128 v[230:233], v145 offset:22528
	ds_read_b128 v[234:237], v145 offset:23552
	global_load_lds_dwordx4 v[146:147], off
	s_add_i32 m0, s94, 0x2000
	s_add_u32 s94, s52, 0x40000
	v_lshl_add_u64 v[158:159], s[52:53], 0, v[134:135]
	s_addc_u32 s95, s53, 0
	s_add_i32 s51, s51, s39
	global_load_lds_dwordx4 v[158:159], off
	v_lshl_add_u64 v[238:239], s[94:95], 0, v[0:1]
	s_mov_b32 m0, s51
	v_lshl_add_u64 v[240:241], s[54:55], 0, v[132:133]
	global_load_lds_dwordx4 v[238:239], off
	v_lshl_add_u64 v[238:239], s[94:95], 0, v[134:135]
	s_add_i32 m0, s51, 0x2000
	s_nop 0
	global_load_lds_dwordx4 v[238:239], off
	v_lshl_add_u64 v[238:239], s[54:55], 0, v[130:131]
	s_mov_b32 m0, s40
	s_nop 0
	global_load_lds_dwordx4 v[238:239], off
	s_mov_b32 m0, s42
	s_nop 0
	global_load_lds_dwordx4 v[240:241], off
	s_waitcnt vmcnt(8)
	s_waitcnt lgkmcnt(0)
	s_barrier
; #define PG8_STAGE(bufoff, gbase, voff) do { _Pragma("unroll") for (int _i = 0; _i < 2; ++_i) \
;         __builtin_amdgcn_global_load_lds((const unsigned*)((const char*)(gbase) + (voff)[_i]), (PG8_LAS unsigned*)(lds + (bufoff) + ldsw + _i * 8192), 16, 0, 0); } while (0)
; #define PG8_LDA(dst, b, h) do { _Pragma("unroll") for (int m = 0; m < 4; ++m) _Pragma("unroll") for (int k = 0; k < 2; ++k) dst[m][k] = *(const PG8_LAS bf16x8*)(lds + PG8_SA(b, h) + aoff + m * 2048 + k * 1024); } while (0)
; #define PG8_LDB(dst, b, h) do { _Pragma("unroll") for (int n = 0; n < 2; ++n) _Pragma("unroll") for (int k = 0; k < 2; ++k) dst[n][k] = *(const PG8_LAS bf16x8*)(lds + PG8_SB(b, h) + boff + n * 2048 + k * 1024); } while (0)
; #define PG8_MMA(ai, bj, At, Bt) do { __builtin_amdgcn_s_setprio(1); _Pragma("unroll") for (int m = 0; m < 4; ++m) _Pragma("unroll") for (int n = 0; n < 2; ++n) _Pragma("unroll") for (int k = 0; k < 2; ++k) \
;         acc[ai][bj][m][n] = __builtin_amdgcn_mfma_f32_16x16x32_bf16(Bt[n][k], At[m][k], acc[ai][bj][m][n], 0, 0, 0); __builtin_amdgcn_s_setprio(0); } while (0)
; #define PG8_WAIT_V(n) asm volatile("s_waitcnt vmcnt(" #n ")" ::: "memory")
; #define PG8_WAIT_L(n) asm volatile("s_waitcnt lgkmcnt(" #n ")" ::: "memory")
; #define PG8_BAR __builtin_amdgcn_s_barrier()
; #define PG8_SCHED __builtin_amdgcn_sched_barrier(0)
; #define PG8_STAGE(bufoff, gbase, voff) do { _Pragma("unroll") for (int _i = 0; _i < 2; ++_i) \
;         __builtin_amdgcn_global_load_lds((const unsigned*)((const char*)(gbase) + (voff)[_i]), (PG8_LAS unsigned*)(lds + (bufoff) + ldsw + _i * 8192), 16, 0, 0); } while (0)
; #define PG8_WAIT_V(n) asm volatile("s_waitcnt vmcnt(" #n ")" ::: "memory")
; #define PG8_WAIT_L(n) asm volatile("s_waitcnt lgkmcnt(" #n ")" ::: "memory")
; template <class Epi, class Sched, bool ALIGN_EPI = false, bool SP2 = false>
; __device__ __forceinline__ void gemm_phase(PG8_LAS unsigned char* lds, const Gemm g, const Sched& S, const Epi& E, const int tid_in) {
;     ...
;             PG8_WAIT_V(8); PG8_WAIT_L(0); PG8_BAR; PG8_MMA(1, 0, At, B0); PG8_MMA(1, 1, At, B1); PG8_BAR; PG8_SCHED;
;             PG8_LDB(B0, 1, 0); PG8_LDB(B1, 1, 1); PG8_SCHED; PG8_LDA(At, 1, 0); PG8_STAGE(PG8_SA(0, 1), a2 + hstep, voffA);
;             PG8_WAIT_V(8); PG8_WAIT_L(0); PG8_BAR; PG8_MMA(0, 0, At, B0); PG8_MMA(0, 1, At, B1); PG8_BAR; PG8_SCHED;
	s_setprio 1
	s_waitcnt lgkmcnt(0)
	v_mfma_f32_16x16x32_bf16 v[62:65], v[150:153], v[206:209], v[62:65]
	v_mfma_f32_16x16x32_bf16 v[58:61], v[172:175], v[206:209], v[58:61]
	v_mfma_f32_16x16x32_bf16 v[46:49], v[150:153], v[214:217], v[46:49]
	v_mfma_f32_16x16x32_bf16 v[42:45], v[172:175], v[214:217], v[42:45]
	v_mfma_f32_16x16x32_bf16 v[30:33], v[150:153], v[222:225], v[30:33]
	v_mfma_f32_16x16x32_bf16 v[26:29], v[172:175], v[222:225], v[26:29]
	v_mfma_f32_16x16x32_bf16 v[14:17], v[150:153], v[230:233], v[14:17]
	v_mfma_f32_16x16x32_bf16 v[10:13], v[172:175], v[230:233], v[10:13]
	v_mfma_f32_16x16x32_bf16 v[62:65], v[154:157], v[210:213], v[62:65]
	v_mfma_f32_16x16x32_bf16 v[58:61], v[176:179], v[210:213], v[58:61]
	v_mfma_f32_16x16x32_bf16 v[46:49], v[154:157], v[218:221], v[46:49]
	v_mfma_f32_16x16x32_bf16 v[42:45], v[176:179], v[218:221], v[42:45]
	v_mfma_f32_16x16x32_bf16 v[30:33], v[154:157], v[226:229], v[30:33]
	v_mfma_f32_16x16x32_bf16 v[26:29], v[176:179], v[226:229], v[26:29]
	v_mfma_f32_16x16x32_bf16 v[14:17], v[154:157], v[234:237], v[14:17]
	v_mfma_f32_16x16x32_bf16 v[10:13], v[176:179], v[234:237], v[10:13]
	s_setprio 0
	s_setprio 1
	v_mfma_f32_16x16x32_bf16 v[54:57], v[180:183], v[206:209], v[54:57]
	v_mfma_f32_16x16x32_bf16 v[50:53], v[188:191], v[206:209], v[50:53]
	v_mfma_f32_16x16x32_bf16 v[38:41], v[180:183], v[214:217], v[38:41]
	v_mfma_f32_16x16x32_bf16 v[34:37], v[188:191], v[214:217], v[34:37]
	v_mfma_f32_16x16x32_bf16 v[22:25], v[180:183], v[222:225], v[22:25]
	v_mfma_f32_16x16x32_bf16 v[18:21], v[188:191], v[222:225], v[18:21]
	v_mfma_f32_16x16x32_bf16 v[6:9], v[180:183], v[230:233], v[6:9]
	v_mfma_f32_16x16x32_bf16 v[2:5], v[188:191], v[230:233], v[2:5]
	v_mfma_f32_16x16x32_bf16 v[54:57], v[184:187], v[210:213], v[54:57]
	v_mfma_f32_16x16x32_bf16 v[50:53], v[202:205], v[210:213], v[50:53]
	v_mfma_f32_16x16x32_bf16 v[38:41], v[184:187], v[218:221], v[38:41]
	v_mfma_f32_16x16x32_bf16 v[34:37], v[202:205], v[218:221], v[34:37]
	v_mfma_f32_16x16x32_bf16 v[22:25], v[184:187], v[226:229], v[22:25]
	v_mfma_f32_16x16x32_bf16 v[18:21], v[202:205], v[226:229], v[18:21]
	v_mfma_f32_16x16x32_bf16 v[6:9], v[184:187], v[234:237], v[6:9]
	v_mfma_f32_16x16x32_bf16 v[2:5], v[202:205], v[234:237], v[2:5]
	s_setprio 0
	s_barrier
	s_add_i32 s51, 0, 0x18000
	v_add_u32_e32 v149, s51, v144
	s_add_i32 s94, 0, 0x1c000
	ds_read_b128 v[150:153], v149
	ds_read_b128 v[154:157], v149 offset:1024
	ds_read_b128 v[172:175], v149 offset:2048
	ds_read_b128 v[176:179], v149 offset:3072
	v_add_u32_e32 v149, s94, v144
	ds_read_b128 v[180:183], v149
	ds_read_b128 v[184:187], v149 offset:1024
	ds_read_b128 v[188:191], v149 offset:2048
	ds_read_b128 v[202:205], v149 offset:3072
	s_add_u32 s54, s54, 0x40000
	s_addc_u32 s55, s55, 0
	s_mov_b32 m0, s44
	v_lshl_add_u64 v[242:243], s[54:55], 0, v[130:131]
	ds_read_b128 v[206:209], v145 offset:32768
	ds_read_b128 v[210:213], v145 offset:33792
	ds_read_b128 v[214:217], v145 offset:34816
	ds_read_b128 v[218:221], v145 offset:35840
	ds_read_b128 v[222:225], v145 offset:36864
	ds_read_b128 v[226:229], v145 offset:37888
	ds_read_b128 v[230:233], v145 offset:38912
	ds_read_b128 v[234:237], v145 offset:39936
	global_load_lds_dwordx4 v[242:243], off
	v_lshl_add_u64 v[242:243], s[54:55], 0, v[132:133]
	s_mov_b32 m0, s45
	s_nop 0
	global_load_lds_dwordx4 v[242:243], off
	s_waitcnt vmcnt(8)
	s_waitcnt lgkmcnt(0)
	s_barrier
	s_setprio 1
	s_waitcnt lgkmcnt(0)
	v_mfma_f32_16x16x32_bf16 v[126:129], v[150:153], v[206:209], v[126:129]
	v_mfma_f32_16x16x32_bf16 v[122:125], v[172:175], v[206:209], v[122:125]
	v_mfma_f32_16x16x32_bf16 v[110:113], v[150:153], v[214:217], v[110:113]
	v_mfma_f32_16x16x32_bf16 v[106:109], v[172:175], v[214:217], v[106:109]
	v_mfma_f32_16x16x32_bf16 v[94:97], v[150:153], v[222:225], v[94:97]
	v_mfma_f32_16x16x32_bf16 v[90:93], v[172:175], v[222:225], v[90:93]
	v_mfma_f32_16x16x32_bf16 v[78:81], v[150:153], v[230:233], v[78:81]
	v_mfma_f32_16x16x32_bf16 v[74:77], v[172:175], v[230:233], v[74:77]
	v_mfma_f32_16x16x32_bf16 v[126:129], v[154:157], v[210:213], v[126:129]
	v_mfma_f32_16x16x32_bf16 v[122:125], v[176:179], v[210:213], v[122:125]
	v_mfma_f32_16x16x32_bf16 v[110:113], v[154:157], v[218:221], v[110:113]
	v_mfma_f32_16x16x32_bf16 v[106:109], v[176:179], v[218:221], v[106:109]
	v_mfma_f32_16x16x32_bf16 v[94:97], v[154:157], v[226:229], v[94:97]
	v_mfma_f32_16x16x32_bf16 v[90:93], v[176:179], v[226:229], v[90:93]
	v_mfma_f32_16x16x32_bf16 v[78:81], v[154:157], v[234:237], v[78:81]
	v_mfma_f32_16x16x32_bf16 v[74:77], v[176:179], v[234:237], v[74:77]
	s_setprio 0
	s_setprio 1
	v_mfma_f32_16x16x32_bf16 v[118:121], v[180:183], v[206:209], v[118:121]
	v_mfma_f32_16x16x32_bf16 v[114:117], v[188:191], v[206:209], v[114:117]
	v_mfma_f32_16x16x32_bf16 v[102:105], v[180:183], v[214:217], v[102:105]
	v_mfma_f32_16x16x32_bf16 v[98:101], v[188:191], v[214:217], v[98:101]
	v_mfma_f32_16x16x32_bf16 v[86:89], v[180:183], v[222:225], v[86:89]
	v_mfma_f32_16x16x32_bf16 v[82:85], v[188:191], v[222:225], v[82:85]
	v_mfma_f32_16x16x32_bf16 v[70:73], v[180:183], v[230:233], v[70:73]
	v_mfma_f32_16x16x32_bf16 v[66:69], v[188:191], v[230:233], v[66:69]
	v_mfma_f32_16x16x32_bf16 v[118:121], v[184:187], v[210:213], v[118:121]
	v_mfma_f32_16x16x32_bf16 v[114:117], v[202:205], v[210:213], v[114:117]
	v_mfma_f32_16x16x32_bf16 v[102:105], v[184:187], v[218:221], v[102:105]
	v_mfma_f32_16x16x32_bf16 v[98:101], v[202:205], v[218:221], v[98:101]
	v_mfma_f32_16x16x32_bf16 v[86:89], v[184:187], v[226:229], v[86:89]
	v_mfma_f32_16x16x32_bf16 v[82:85], v[202:205], v[226:229], v[82:85]
	v_mfma_f32_16x16x32_bf16 v[70:73], v[184:187], v[234:237], v[70:73]
	v_mfma_f32_16x16x32_bf16 v[66:69], v[202:205], v[234:237], v[66:69]
	s_setprio 0
	s_barrier
; #define PG8_STAGE(bufoff, gbase, voff) do { _Pragma("unroll") for (int _i = 0; _i < 2; ++_i) \
;         __builtin_amdgcn_global_load_lds((const unsigned*)((const char*)(gbase) + (voff)[_i]), (PG8_LAS unsigned*)(lds + (bufoff) + ldsw + _i * 8192), 16, 0, 0); } while (0)
; #define PG8_LDA(dst, b, h) do { _Pragma("unroll") for (int m = 0; m < 4; ++m) _Pragma("unroll") for (int k = 0; k < 2; ++k) dst[m][k] = *(const PG8_LAS bf16x8*)(lds + PG8_SA(b, h) + aoff + m * 2048 + k * 1024); } while (0)
; #define PG8_MMA(ai, bj, At, Bt) do { __builtin_amdgcn_s_setprio(1); _Pragma("unroll") for (int m = 0; m < 4; ++m) _Pragma("unroll") for (int n = 0; n < 2; ++n) _Pragma("unroll") for (int k = 0; k < 2; ++k) \
;         acc[ai][bj][m][n] = __builtin_amdgcn_mfma_f32_16x16x32_bf16(Bt[n][k], At[m][k], acc[ai][bj][m][n], 0, 0, 0); __builtin_amdgcn_s_setprio(0); } while (0)
; #define PG8_WAIT_V(n) asm volatile("s_waitcnt vmcnt(" #n ")" ::: "memory")
; #define PG8_WAIT_L(n) asm volatile("s_waitcnt lgkmcnt(" #n ")" ::: "memory")
; #define PG8_BAR __builtin_amdgcn_s_barrier()
; #define PG8_SCHED __builtin_amdgcn_sched_barrier(0)
; #define PG8_STAGE(bufoff, gbase, voff) do { _Pragma("unroll") for (int _i = 0; _i < 2; ++_i) \
;         __builtin_amdgcn_global_load_lds((const unsigned*)((const char*)(gbase) + (voff)[_i]), (PG8_LAS unsigned*)(lds + (bufoff) + ldsw + _i * 8192), 16, 0, 0); } while (0)
; #define PG8_WAIT_V(n) asm volatile("s_waitcnt vmcnt(" #n ")" ::: "memory")
; #define PG8_BAR __builtin_amdgcn_s_barrier()
; template <class Epi, class Sched, bool ALIGN_EPI = false, bool SP2 = false>
; __device__ __forceinline__ void gemm_phase(PG8_LAS unsigned char* lds, const Gemm g, const Sched& S, const Epi& E, const int tid_in) {
;     ...
;             PG8_LDA(At, 1, 1); PG8_STAGE(PG8_SB(1, 0), b3, voffB); PG8_STAGE(PG8_SB(1, 1), b3 + hstep, voffB); PG8_STAGE(PG8_SA(1, 0), a3, voffA);
;             PG8_WAIT_V(8); PG8_WAIT_L(0); PG8_BAR; PG8_MMA(1, 0, At, B0); PG8_MMA(1, 1, At, B1); PG8_BAR; PG8_SCHED;
;     ...
;         if (!has_next) break;
; #pragma unroll
;         for (int a = 0; a < 2; ++a)
; #pragma unroll
;             for (int b = 0; b < 2; ++b)
; #pragma unroll
;                 for (int m = 0; m < 4; ++m)
; #pragma unroll
;                     for (int n = 0; n < 2; ++n) acc[a][b][m][n] = (f32x4){0.f, 0.f, 0.f, 0.f};
;         cur = nxt; cA = nA; cB = nB; ++ui;
	s_add_i32 s51, s51, s39
	v_lshl_add_u64 v[146:147], v[146:147], 0, s[82:83]
	s_mov_b32 m0, s51
	ds_read_b128 v[206:209], v145 offset:49152
	ds_read_b128 v[210:213], v145 offset:50176
	ds_read_b128 v[214:217], v145 offset:51200
	ds_read_b128 v[218:221], v145 offset:52224
	ds_read_b128 v[222:225], v145 offset:53248
	ds_read_b128 v[226:229], v145 offset:54272
	ds_read_b128 v[230:233], v145 offset:55296
	ds_read_b128 v[234:237], v145 offset:56320
	global_load_lds_dwordx4 v[146:147], off
	s_add_i32 m0, s51, 0x2000
	s_add_u32 s52, s52, 0x40080
	v_lshl_add_u64 v[146:147], v[158:159], 0, s[82:83]
	s_addc_u32 s53, s53, 0
	s_add_i32 s51, s94, s39
	global_load_lds_dwordx4 v[146:147], off
	v_lshl_add_u64 v[146:147], s[52:53], 0, v[0:1]
	s_mov_b32 m0, s51
	s_nop 0
	global_load_lds_dwordx4 v[146:147], off
	v_lshl_add_u64 v[146:147], s[52:53], 0, v[134:135]
	s_add_i32 m0, s51, 0x2000
	s_nop 0
	global_load_lds_dwordx4 v[146:147], off
	v_lshl_add_u64 v[146:147], v[238:239], 0, s[82:83]
	s_mov_b32 m0, s46
	s_nop 0
	global_load_lds_dwordx4 v[146:147], off
	v_lshl_add_u64 v[146:147], v[240:241], 0, s[82:83]
	s_mov_b32 m0, s47
	s_nop 0
	global_load_lds_dwordx4 v[146:147], off
	s_waitcnt vmcnt(8)
	s_waitcnt lgkmcnt(0)
	s_barrier
	s_setprio 1
	s_waitcnt lgkmcnt(0)
	v_mfma_f32_16x16x32_bf16 v[62:65], v[150:153], v[206:209], v[62:65]
	v_mfma_f32_16x16x32_bf16 v[58:61], v[172:175], v[206:209], v[58:61]
	v_mfma_f32_16x16x32_bf16 v[46:49], v[150:153], v[214:217], v[46:49]
	v_mfma_f32_16x16x32_bf16 v[42:45], v[172:175], v[214:217], v[42:45]
	v_mfma_f32_16x16x32_bf16 v[30:33], v[150:153], v[222:225], v[30:33]
	v_mfma_f32_16x16x32_bf16 v[26:29], v[172:175], v[222:225], v[26:29]
	v_mfma_f32_16x16x32_bf16 v[14:17], v[150:153], v[230:233], v[14:17]
	v_mfma_f32_16x16x32_bf16 v[10:13], v[172:175], v[230:233], v[10:13]
	v_mfma_f32_16x16x32_bf16 v[62:65], v[154:157], v[210:213], v[62:65]
	v_mfma_f32_16x16x32_bf16 v[58:61], v[176:179], v[210:213], v[58:61]
	v_mfma_f32_16x16x32_bf16 v[46:49], v[154:157], v[218:221], v[46:49]
	v_mfma_f32_16x16x32_bf16 v[42:45], v[176:179], v[218:221], v[42:45]
	v_mfma_f32_16x16x32_bf16 v[30:33], v[154:157], v[226:229], v[30:33]
	v_mfma_f32_16x16x32_bf16 v[26:29], v[176:179], v[226:229], v[26:29]
	v_mfma_f32_16x16x32_bf16 v[14:17], v[154:157], v[234:237], v[14:17]
	v_mfma_f32_16x16x32_bf16 v[10:13], v[176:179], v[234:237], v[10:13]
	s_setprio 0
	s_setprio 1
	v_mfma_f32_16x16x32_bf16 v[54:57], v[180:183], v[206:209], v[54:57]
	v_mfma_f32_16x16x32_bf16 v[50:53], v[188:191], v[206:209], v[50:53]
	v_mfma_f32_16x16x32_bf16 v[38:41], v[180:183], v[214:217], v[38:41]
	v_mfma_f32_16x16x32_bf16 v[34:37], v[188:191], v[214:217], v[34:37]
	v_mfma_f32_16x16x32_bf16 v[22:25], v[180:183], v[222:225], v[22:25]
	v_mfma_f32_16x16x32_bf16 v[18:21], v[188:191], v[222:225], v[18:21]
	v_mfma_f32_16x16x32_bf16 v[6:9], v[180:183], v[230:233], v[6:9]
	v_mfma_f32_16x16x32_bf16 v[2:5], v[188:191], v[230:233], v[2:5]
	v_mfma_f32_16x16x32_bf16 v[54:57], v[184:187], v[210:213], v[54:57]
	v_mfma_f32_16x16x32_bf16 v[50:53], v[202:205], v[210:213], v[50:53]
	v_mfma_f32_16x16x32_bf16 v[38:41], v[184:187], v[218:221], v[38:41]
	v_mfma_f32_16x16x32_bf16 v[34:37], v[202:205], v[218:221], v[34:37]
	v_mfma_f32_16x16x32_bf16 v[22:25], v[184:187], v[226:229], v[22:25]
	v_mfma_f32_16x16x32_bf16 v[18:21], v[202:205], v[226:229], v[18:21]
	v_mfma_f32_16x16x32_bf16 v[6:9], v[184:187], v[234:237], v[6:9]
	v_mfma_f32_16x16x32_bf16 v[2:5], v[202:205], v[234:237], v[2:5]
	s_add_i32 s93, s93, 2
	s_add_u32 s90, s90, 0x100
	s_addc_u32 s91, s91, 0
	s_cmp_gt_u32 s93, 13
	s_setprio 0
	s_barrier
	s_cbranch_scc0 .LBB0_31
	s_add_u32 s52, s57, 0xffffff00
	s_addc_u32 s53, s68, -1
	s_andn2_b64 vcc, exec, s[0:1]
	s_cbranch_vccnz .LBB0_22
	v_mov_b32_e32 v2, 0
	s_mov_b32 s14, s70
	s_mov_b32 s34, s66
	s_mov_b64 s[64:65], s[88:89]
	s_mov_b32 s49, s56
	v_mov_b32_e32 v3, v2
	v_mov_b32_e32 v4, v2
	v_mov_b32_e32 v5, v2
	v_mov_b32_e32 v6, v2
	v_mov_b32_e32 v7, v2
	v_mov_b32_e32 v8, v2
	v_mov_b32_e32 v9, v2
	v_mov_b32_e32 v18, v2
	v_mov_b32_e32 v19, v2
	v_mov_b32_e32 v20, v2
	v_mov_b32_e32 v21, v2
	v_mov_b32_e32 v22, v2
	v_mov_b32_e32 v23, v2
	v_mov_b32_e32 v24, v2
	v_mov_b32_e32 v25, v2
	v_mov_b32_e32 v34, v2
	v_mov_b32_e32 v35, v2
	v_mov_b32_e32 v36, v2
	v_mov_b32_e32 v37, v2
	v_mov_b32_e32 v38, v2
	v_mov_b32_e32 v39, v2
	v_mov_b32_e32 v40, v2
	v_mov_b32_e32 v41, v2
	v_mov_b32_e32 v50, v2
	v_mov_b32_e32 v51, v2
	v_mov_b32_e32 v52, v2
	v_mov_b32_e32 v53, v2
	v_mov_b32_e32 v54, v2
	v_mov_b32_e32 v55, v2
	v_mov_b32_e32 v56, v2
	v_mov_b32_e32 v57, v2
	v_mov_b32_e32 v10, v2
	v_mov_b32_e32 v11, v2
	v_mov_b32_e32 v12, v2
	v_mov_b32_e32 v13, v2
	v_mov_b32_e32 v14, v2
	v_mov_b32_e32 v15, v2
	v_mov_b32_e32 v16, v2
	v_mov_b32_e32 v17, v2
	v_mov_b32_e32 v26, v2
	v_mov_b32_e32 v27, v2
	v_mov_b32_e32 v28, v2
	v_mov_b32_e32 v29, v2
	v_mov_b32_e32 v30, v2
	v_mov_b32_e32 v31, v2
	v_mov_b32_e32 v32, v2
	v_mov_b32_e32 v33, v2
	v_mov_b32_e32 v42, v2
	v_mov_b32_e32 v43, v2
	v_mov_b32_e32 v44, v2
	v_mov_b32_e32 v45, v2
	v_mov_b32_e32 v46, v2
	v_mov_b32_e32 v47, v2
	v_mov_b32_e32 v48, v2
	v_mov_b32_e32 v49, v2
	v_mov_b32_e32 v58, v2
	v_mov_b32_e32 v59, v2
	v_mov_b32_e32 v60, v2
	v_mov_b32_e32 v61, v2
	v_mov_b32_e32 v62, v2
	v_mov_b32_e32 v63, v2
	v_mov_b32_e32 v64, v2
	v_mov_b32_e32 v65, v2
	v_mov_b32_e32 v66, v2
	v_mov_b32_e32 v67, v2
	v_mov_b32_e32 v68, v2
	v_mov_b32_e32 v69, v2
	v_mov_b32_e32 v70, v2
	v_mov_b32_e32 v71, v2
	v_mov_b32_e32 v72, v2
	v_mov_b32_e32 v73, v2
	v_mov_b32_e32 v82, v2
	v_mov_b32_e32 v83, v2
	v_mov_b32_e32 v84, v2
	v_mov_b32_e32 v85, v2
	v_mov_b32_e32 v86, v2
	v_mov_b32_e32 v87, v2
	v_mov_b32_e32 v88, v2
	v_mov_b32_e32 v89, v2
	v_mov_b32_e32 v98, v2
	v_mov_b32_e32 v99, v2
	v_mov_b32_e32 v100, v2
	v_mov_b32_e32 v101, v2
	v_mov_b32_e32 v102, v2
	v_mov_b32_e32 v103, v2
	v_mov_b32_e32 v104, v2
	v_mov_b32_e32 v105, v2
	v_mov_b32_e32 v114, v2
	v_mov_b32_e32 v115, v2
	v_mov_b32_e32 v116, v2
	v_mov_b32_e32 v117, v2
	v_mov_b32_e32 v118, v2
	v_mov_b32_e32 v119, v2
	v_mov_b32_e32 v120, v2
	v_mov_b32_e32 v121, v2
	v_mov_b32_e32 v74, v2
	v_mov_b32_e32 v75, v2
	v_mov_b32_e32 v76, v2
	v_mov_b32_e32 v77, v2
	v_mov_b32_e32 v78, v2
	v_mov_b32_e32 v79, v2
	v_mov_b32_e32 v80, v2
	v_mov_b32_e32 v81, v2
	v_mov_b32_e32 v90, v2
	v_mov_b32_e32 v91, v2
	v_mov_b32_e32 v92, v2
	v_mov_b32_e32 v93, v2
	v_mov_b32_e32 v94, v2
	v_mov_b32_e32 v95, v2
	v_mov_b32_e32 v96, v2
	v_mov_b32_e32 v97, v2
	v_mov_b32_e32 v106, v2
	v_mov_b32_e32 v107, v2
	v_mov_b32_e32 v108, v2
	v_mov_b32_e32 v109, v2
	v_mov_b32_e32 v110, v2
	v_mov_b32_e32 v111, v2
	v_mov_b32_e32 v112, v2
	v_mov_b32_e32 v113, v2
	v_mov_b32_e32 v122, v2
	v_mov_b32_e32 v123, v2
	v_mov_b32_e32 v124, v2
	v_mov_b32_e32 v125, v2
	v_mov_b32_e32 v126, v2
	v_mov_b32_e32 v127, v2
	v_mov_b32_e32 v128, v2
	v_mov_b32_e32 v129, v2
	s_andn2_b64 vcc, exec, s[4:5]
	s_cbranch_vccnz .LBB0_23

; #define PG8_STAGE(bufoff, gbase, voff) do { _Pragma("unroll") for (int _i = 0; _i < 2; ++_i) \
;         __builtin_amdgcn_global_load_lds((const unsigned*)((const char*)(gbase) + (voff)[_i]), (PG8_LAS unsigned*)(lds + (bufoff) + ldsw + _i * 8192), 16, 0, 0); } while (0)
; #define PG8_LDA(dst, b, h) do { _Pragma("unroll") for (int m = 0; m < 4; ++m) _Pragma("unroll") for (int k = 0; k < 2; ++k) dst[m][k] = *(const PG8_LAS bf16x8*)(lds + PG8_SA(b, h) + aoff + m * 2048 + k * 1024); } while (0)
; #define PG8_LDB(dst, b, h) do { _Pragma("unroll") for (int n = 0; n < 2; ++n) _Pragma("unroll") for (int k = 0; k < 2; ++k) dst[n][k] = *(const PG8_LAS bf16x8*)(lds + PG8_SB(b, h) + boff + n * 2048 + k * 1024); } while (0)
; #define PG8_MMA(ai, bj, At, Bt) do { __builtin_amdgcn_s_setprio(1); _Pragma("unroll") for (int m = 0; m < 4; ++m) _Pragma("unroll") for (int n = 0; n < 2; ++n) _Pragma("unroll") for (int k = 0; k < 2; ++k) \
;         acc[ai][bj][m][n] = __builtin_amdgcn_mfma_f32_16x16x32_bf16(Bt[n][k], At[m][k], acc[ai][bj][m][n], 0, 0, 0); __builtin_amdgcn_s_setprio(0); } while (0)
; #define PG8_WAIT_V(n) asm volatile("s_waitcnt vmcnt(" #n ")" ::: "memory")
; #define PG8_WAIT_L(n) asm volatile("s_waitcnt lgkmcnt(" #n ")" ::: "memory")
; #define PG8_BAR __builtin_amdgcn_s_barrier()
; #define PG8_SCHED __builtin_amdgcn_sched_barrier(0)
; #define PG8_STAGE(bufoff, gbase, voff) do { _Pragma("unroll") for (int _i = 0; _i < 2; ++_i) \
;         __builtin_amdgcn_global_load_lds((const unsigned*)((const char*)(gbase) + (voff)[_i]), (PG8_LAS unsigned*)(lds + (bufoff) + ldsw + _i * 8192), 16, 0, 0); } while (0)
; #define PG8_BAR __builtin_amdgcn_s_barrier()
; template <class Epi, class Sched, bool ALIGN_EPI = false, bool SP2 = false>
; __device__ __forceinline__ void gemm_phase(PG8_LAS unsigned char* lds, const Gemm g, const Sched& S, const Epi& E, const int tid_in) {
;     ...
;             PG8_LDB(B0, 0, 0); PG8_LDB(B1, 0, 1); PG8_SCHED; PG8_LDA(At, 0, 0); PG8_STAGE(PG8_SA(1, 1), a1 + hstep, voffA);
;             PG8_WAIT_V(8); PG8_WAIT_L(0); PG8_BAR; PG8_MMA(0, 0, At, B0); PG8_MMA(0, 1, At, B1); PG8_BAR; PG8_SCHED;
;             PG8_LDA(At, 0, 1); PG8_STAGE(PG8_SB(0, 0), b2, voffB); PG8_STAGE(PG8_SB(0, 1), b2 + hstep, voffB); PG8_STAGE(PG8_SA(0, 0), a2, voffA);
;             PG8_WAIT_V(8); PG8_WAIT_L(0); PG8_BAR; PG8_MMA(1, 0, At, B0); PG8_MMA(1, 1, At, B1); PG8_BAR; PG8_SCHED;
.LBB0_221:
	s_add_u32 s14, s8, 0xfffc0080
	s_addc_u32 s15, s9, -1
	s_add_i32 s68, 0, 0x10000
	s_cmp_eq_u32 vcc_hi, 12
	s_cselect_b32 s55, s11, s15
	s_cselect_b32 s54, s80, s14
	v_add_u32_e32 v0, s68, v141
	s_cselect_b32 s15, s35, vcc_lo
	s_cselect_b32 s14, s89, s91
	s_add_i32 s51, 0, 0x14000
	ds_read_b128 v[150:153], v0
	ds_read_b128 v[154:157], v0 offset:1024
	ds_read_b128 v[172:175], v0 offset:2048
	ds_read_b128 v[176:179], v0 offset:3072
	v_add_u32_e32 v0, s51, v141
	ds_read_b128 v[180:183], v0
	ds_read_b128 v[184:187], v0 offset:1024
	ds_read_b128 v[188:191], v0 offset:2048
	ds_read_b128 v[202:205], v0 offset:3072
	v_lshl_add_u64 v[238:239], s[8:9], 0, v[146:147]
	s_add_i32 m0, s45, 0xc000
	ds_read_b128 v[206:209], v159
	ds_read_b128 v[210:213], v159 offset:1024
	ds_read_b128 v[214:217], v159 offset:2048
	ds_read_b128 v[218:221], v159 offset:3072
	ds_read_b128 v[222:225], v159 offset:4096
	ds_read_b128 v[226:229], v159 offset:5120
	ds_read_b128 v[230:233], v159 offset:6144
	ds_read_b128 v[234:237], v159 offset:7168
	global_load_lds_dwordx4 v[238:239], off
	v_lshl_add_u64 v[238:239], s[8:9], 0, v[148:149]
	s_add_i32 m0, s45, 0xe000
	s_nop 0
	global_load_lds_dwordx4 v[238:239], off
	s_waitcnt vmcnt(8)
	s_waitcnt lgkmcnt(0)
	s_barrier
	s_setprio 1
	s_waitcnt lgkmcnt(0)
	v_mfma_f32_16x16x32_bf16 v[126:129], v[150:153], v[206:209], v[126:129]
	v_mfma_f32_16x16x32_bf16 v[118:121], v[172:175], v[206:209], v[118:121]
	v_mfma_f32_16x16x32_bf16 v[110:113], v[150:153], v[214:217], v[110:113]
	v_mfma_f32_16x16x32_bf16 v[102:105], v[172:175], v[214:217], v[102:105]
	v_mfma_f32_16x16x32_bf16 v[94:97], v[150:153], v[222:225], v[94:97]
	v_mfma_f32_16x16x32_bf16 v[86:89], v[172:175], v[222:225], v[86:89]
	v_mfma_f32_16x16x32_bf16 v[78:81], v[150:153], v[230:233], v[78:81]
	v_mfma_f32_16x16x32_bf16 v[70:73], v[172:175], v[230:233], v[70:73]
	v_mfma_f32_16x16x32_bf16 v[126:129], v[154:157], v[210:213], v[126:129]
	v_mfma_f32_16x16x32_bf16 v[118:121], v[176:179], v[210:213], v[118:121]
	v_mfma_f32_16x16x32_bf16 v[110:113], v[154:157], v[218:221], v[110:113]
	v_mfma_f32_16x16x32_bf16 v[102:105], v[176:179], v[218:221], v[102:105]
	v_mfma_f32_16x16x32_bf16 v[94:97], v[154:157], v[226:229], v[94:97]
	v_mfma_f32_16x16x32_bf16 v[86:89], v[176:179], v[226:229], v[86:89]
	v_mfma_f32_16x16x32_bf16 v[78:81], v[154:157], v[234:237], v[78:81]
	v_mfma_f32_16x16x32_bf16 v[70:73], v[176:179], v[234:237], v[70:73]
	s_setprio 0
	s_setprio 1
	v_mfma_f32_16x16x32_bf16 v[122:125], v[180:183], v[206:209], v[122:125]
	v_mfma_f32_16x16x32_bf16 v[114:117], v[188:191], v[206:209], v[114:117]
	v_mfma_f32_16x16x32_bf16 v[106:109], v[180:183], v[214:217], v[106:109]
	v_mfma_f32_16x16x32_bf16 v[98:101], v[188:191], v[214:217], v[98:101]
	v_mfma_f32_16x16x32_bf16 v[90:93], v[180:183], v[222:225], v[90:93]
	v_mfma_f32_16x16x32_bf16 v[82:85], v[188:191], v[222:225], v[82:85]
	v_mfma_f32_16x16x32_bf16 v[74:77], v[180:183], v[230:233], v[74:77]
	v_mfma_f32_16x16x32_bf16 v[66:69], v[188:191], v[230:233], v[66:69]
	v_mfma_f32_16x16x32_bf16 v[122:125], v[184:187], v[210:213], v[122:125]
	v_mfma_f32_16x16x32_bf16 v[114:117], v[202:205], v[210:213], v[114:117]
	v_mfma_f32_16x16x32_bf16 v[106:109], v[184:187], v[218:221], v[106:109]
	v_mfma_f32_16x16x32_bf16 v[98:101], v[202:205], v[218:221], v[98:101]
	v_mfma_f32_16x16x32_bf16 v[90:93], v[184:187], v[226:229], v[90:93]
	v_mfma_f32_16x16x32_bf16 v[82:85], v[202:205], v[226:229], v[82:85]
	v_mfma_f32_16x16x32_bf16 v[74:77], v[184:187], v[234:237], v[74:77]
	v_mfma_f32_16x16x32_bf16 v[66:69], v[202:205], v[234:237], v[66:69]
	s_setprio 0
	s_barrier
	s_add_i32 s68, s68, s44
	v_lshl_add_u64 v[238:239], s[14:15], 0, v[132:133]
	s_mov_b32 m0, s68
	ds_read_b128 v[206:209], v159 offset:16384
	ds_read_b128 v[210:213], v159 offset:17408
	ds_read_b128 v[214:217], v159 offset:18432
	ds_read_b128 v[218:221], v159 offset:19456
	ds_read_b128 v[222:225], v159 offset:20480
	ds_read_b128 v[226:229], v159 offset:21504
	ds_read_b128 v[230:233], v159 offset:22528
	ds_read_b128 v[234:237], v159 offset:23552
	global_load_lds_dwordx4 v[238:239], off
	s_add_i32 m0, s68, 0x2000
	s_add_u32 s68, s14, 0x40000
	v_lshl_add_u64 v[240:241], s[14:15], 0, v[136:137]
	s_addc_u32 s69, s15, 0
	s_add_i32 s51, s51, s44
	global_load_lds_dwordx4 v[240:241], off
	v_lshl_add_u64 v[242:243], s[68:69], 0, v[132:133]
	s_mov_b32 m0, s51
	v_lshl_add_u64 v[244:245], s[54:55], 0, v[134:135]
	global_load_lds_dwordx4 v[242:243], off
	v_lshl_add_u64 v[242:243], s[68:69], 0, v[136:137]
	s_add_i32 m0, s51, 0x2000
	s_nop 0
	global_load_lds_dwordx4 v[242:243], off
	v_lshl_add_u64 v[242:243], s[54:55], 0, v[130:131]
	s_mov_b32 m0, s45
	s_nop 0
	global_load_lds_dwordx4 v[242:243], off
	s_mov_b32 m0, s47
	s_nop 0
	global_load_lds_dwordx4 v[244:245], off
	s_waitcnt vmcnt(8)
	s_waitcnt lgkmcnt(0)
	s_barrier
; #define PG8_STAGE(bufoff, gbase, voff) do { _Pragma("unroll") for (int _i = 0; _i < 2; ++_i) \
;         __builtin_amdgcn_global_load_lds((const unsigned*)((const char*)(gbase) + (voff)[_i]), (PG8_LAS unsigned*)(lds + (bufoff) + ldsw + _i * 8192), 16, 0, 0); } while (0)
; #define PG8_LDA(dst, b, h) do { _Pragma("unroll") for (int m = 0; m < 4; ++m) _Pragma("unroll") for (int k = 0; k < 2; ++k) dst[m][k] = *(const PG8_LAS bf16x8*)(lds + PG8_SA(b, h) + aoff + m * 2048 + k * 1024); } while (0)
; #define PG8_LDB(dst, b, h) do { _Pragma("unroll") for (int n = 0; n < 2; ++n) _Pragma("unroll") for (int k = 0; k < 2; ++k) dst[n][k] = *(const PG8_LAS bf16x8*)(lds + PG8_SB(b, h) + boff + n * 2048 + k * 1024); } while (0)
; #define PG8_MMA(ai, bj, At, Bt) do { __builtin_amdgcn_s_setprio(1); _Pragma("unroll") for (int m = 0; m < 4; ++m) _Pragma("unroll") for (int n = 0; n < 2; ++n) _Pragma("unroll") for (int k = 0; k < 2; ++k) \
;         acc[ai][bj][m][n] = __builtin_amdgcn_mfma_f32_16x16x32_bf16(Bt[n][k], At[m][k], acc[ai][bj][m][n], 0, 0, 0); __builtin_amdgcn_s_setprio(0); } while (0)
; #define PG8_WAIT_V(n) asm volatile("s_waitcnt vmcnt(" #n ")" ::: "memory")
; #define PG8_WAIT_L(n) asm volatile("s_waitcnt lgkmcnt(" #n ")" ::: "memory")
; #define PG8_BAR __builtin_amdgcn_s_barrier()
; #define PG8_SCHED __builtin_amdgcn_sched_barrier(0)
; #define PG8_STAGE(bufoff, gbase, voff) do { _Pragma("unroll") for (int _i = 0; _i < 2; ++_i) \
;         __builtin_amdgcn_global_load_lds((const unsigned*)((const char*)(gbase) + (voff)[_i]), (PG8_LAS unsigned*)(lds + (bufoff) + ldsw + _i * 8192), 16, 0, 0); } while (0)
; #define PG8_WAIT_V(n) asm volatile("s_waitcnt vmcnt(" #n ")" ::: "memory")
; #define PG8_WAIT_L(n) asm volatile("s_waitcnt lgkmcnt(" #n ")" ::: "memory")
; template <class Epi, class Sched, bool ALIGN_EPI = false, bool SP2 = false>
; __device__ __forceinline__ void gemm_phase(PG8_LAS unsigned char* lds, const Gemm g, const Sched& S, const Epi& E, const int tid_in) {
;     ...
;             PG8_WAIT_V(8); PG8_WAIT_L(0); PG8_BAR; PG8_MMA(1, 0, At, B0); PG8_MMA(1, 1, At, B1); PG8_BAR; PG8_SCHED;
;             PG8_LDB(B0, 1, 0); PG8_LDB(B1, 1, 1); PG8_SCHED; PG8_LDA(At, 1, 0); PG8_STAGE(PG8_SA(0, 1), a2 + hstep, voffA);
;             PG8_WAIT_V(8); PG8_WAIT_L(0); PG8_BAR; PG8_MMA(0, 0, At, B0); PG8_MMA(0, 1, At, B1); PG8_BAR; PG8_SCHED;
	s_setprio 1
	s_waitcnt lgkmcnt(0)
	v_mfma_f32_16x16x32_bf16 v[62:65], v[150:153], v[206:209], v[62:65]
	v_mfma_f32_16x16x32_bf16 v[54:57], v[172:175], v[206:209], v[54:57]
	v_mfma_f32_16x16x32_bf16 v[46:49], v[150:153], v[214:217], v[46:49]
	v_mfma_f32_16x16x32_bf16 v[38:41], v[172:175], v[214:217], v[38:41]
	v_mfma_f32_16x16x32_bf16 v[30:33], v[150:153], v[222:225], v[30:33]
	v_mfma_f32_16x16x32_bf16 v[22:25], v[172:175], v[222:225], v[22:25]
	v_mfma_f32_16x16x32_bf16 v[14:17], v[150:153], v[230:233], v[14:17]
	v_mfma_f32_16x16x32_bf16 v[6:9], v[172:175], v[230:233], v[6:9]
	v_mfma_f32_16x16x32_bf16 v[62:65], v[154:157], v[210:213], v[62:65]
	v_mfma_f32_16x16x32_bf16 v[54:57], v[176:179], v[210:213], v[54:57]
	v_mfma_f32_16x16x32_bf16 v[46:49], v[154:157], v[218:221], v[46:49]
	v_mfma_f32_16x16x32_bf16 v[38:41], v[176:179], v[218:221], v[38:41]
	v_mfma_f32_16x16x32_bf16 v[30:33], v[154:157], v[226:229], v[30:33]
	v_mfma_f32_16x16x32_bf16 v[22:25], v[176:179], v[226:229], v[22:25]
	v_mfma_f32_16x16x32_bf16 v[14:17], v[154:157], v[234:237], v[14:17]
	v_mfma_f32_16x16x32_bf16 v[6:9], v[176:179], v[234:237], v[6:9]
	s_setprio 0
	s_setprio 1
	v_mfma_f32_16x16x32_bf16 v[58:61], v[180:183], v[206:209], v[58:61]
	v_mfma_f32_16x16x32_bf16 v[50:53], v[188:191], v[206:209], v[50:53]
	v_mfma_f32_16x16x32_bf16 v[42:45], v[180:183], v[214:217], v[42:45]
	v_mfma_f32_16x16x32_bf16 v[34:37], v[188:191], v[214:217], v[34:37]
	v_mfma_f32_16x16x32_bf16 v[26:29], v[180:183], v[222:225], v[26:29]
	v_mfma_f32_16x16x32_bf16 v[18:21], v[188:191], v[222:225], v[18:21]
	v_mfma_f32_16x16x32_bf16 v[10:13], v[180:183], v[230:233], v[10:13]
	v_mfma_f32_16x16x32_bf16 v[2:5], v[188:191], v[230:233], v[2:5]
	v_mfma_f32_16x16x32_bf16 v[58:61], v[184:187], v[210:213], v[58:61]
	v_mfma_f32_16x16x32_bf16 v[50:53], v[202:205], v[210:213], v[50:53]
	v_mfma_f32_16x16x32_bf16 v[42:45], v[184:187], v[218:221], v[42:45]
	v_mfma_f32_16x16x32_bf16 v[34:37], v[202:205], v[218:221], v[34:37]
	v_mfma_f32_16x16x32_bf16 v[26:29], v[184:187], v[226:229], v[26:29]
	v_mfma_f32_16x16x32_bf16 v[18:21], v[202:205], v[226:229], v[18:21]
	v_mfma_f32_16x16x32_bf16 v[10:13], v[184:187], v[234:237], v[10:13]
	v_mfma_f32_16x16x32_bf16 v[2:5], v[202:205], v[234:237], v[2:5]
	s_setprio 0
	s_barrier
	s_add_i32 s51, 0, 0x18000
	v_add_u32_e32 v0, s51, v141
	s_add_i32 s68, 0, 0x1c000
	ds_read_b128 v[150:153], v0
	ds_read_b128 v[154:157], v0 offset:1024
	ds_read_b128 v[172:175], v0 offset:2048
	ds_read_b128 v[176:179], v0 offset:3072
	v_add_u32_e32 v0, s68, v141
	ds_read_b128 v[180:183], v0
	ds_read_b128 v[184:187], v0 offset:1024
	ds_read_b128 v[188:191], v0 offset:2048
	ds_read_b128 v[202:205], v0 offset:3072
	s_add_u32 s54, s54, 0x40000
	s_addc_u32 s55, s55, 0
	s_mov_b32 m0, s56
	v_lshl_add_u64 v[246:247], s[54:55], 0, v[130:131]
	ds_read_b128 v[206:209], v159 offset:32768
	ds_read_b128 v[210:213], v159 offset:33792
	ds_read_b128 v[214:217], v159 offset:34816
	ds_read_b128 v[218:221], v159 offset:35840
	ds_read_b128 v[222:225], v159 offset:36864
	ds_read_b128 v[226:229], v159 offset:37888
	ds_read_b128 v[230:233], v159 offset:38912
	ds_read_b128 v[234:237], v159 offset:39936
	global_load_lds_dwordx4 v[246:247], off
	v_lshl_add_u64 v[246:247], s[54:55], 0, v[134:135]
	s_mov_b32 m0, s57
	s_nop 0
	global_load_lds_dwordx4 v[246:247], off
	s_waitcnt vmcnt(8)
	s_waitcnt lgkmcnt(0)
	s_barrier
	s_setprio 1
	s_waitcnt lgkmcnt(0)
	v_mfma_f32_16x16x32_bf16 v[126:129], v[150:153], v[206:209], v[126:129]
	v_mfma_f32_16x16x32_bf16 v[118:121], v[172:175], v[206:209], v[118:121]
	v_mfma_f32_16x16x32_bf16 v[110:113], v[150:153], v[214:217], v[110:113]
	v_mfma_f32_16x16x32_bf16 v[102:105], v[172:175], v[214:217], v[102:105]
	v_mfma_f32_16x16x32_bf16 v[94:97], v[150:153], v[222:225], v[94:97]
	v_mfma_f32_16x16x32_bf16 v[86:89], v[172:175], v[222:225], v[86:89]
	v_mfma_f32_16x16x32_bf16 v[78:81], v[150:153], v[230:233], v[78:81]
	v_mfma_f32_16x16x32_bf16 v[70:73], v[172:175], v[230:233], v[70:73]
	v_mfma_f32_16x16x32_bf16 v[126:129], v[154:157], v[210:213], v[126:129]
	v_mfma_f32_16x16x32_bf16 v[118:121], v[176:179], v[210:213], v[118:121]
	v_mfma_f32_16x16x32_bf16 v[110:113], v[154:157], v[218:221], v[110:113]
	v_mfma_f32_16x16x32_bf16 v[102:105], v[176:179], v[218:221], v[102:105]
	v_mfma_f32_16x16x32_bf16 v[94:97], v[154:157], v[226:229], v[94:97]
	v_mfma_f32_16x16x32_bf16 v[86:89], v[176:179], v[226:229], v[86:89]
	v_mfma_f32_16x16x32_bf16 v[78:81], v[154:157], v[234:237], v[78:81]
	v_mfma_f32_16x16x32_bf16 v[70:73], v[176:179], v[234:237], v[70:73]
	s_setprio 0
	s_setprio 1
	v_mfma_f32_16x16x32_bf16 v[122:125], v[180:183], v[206:209], v[122:125]
	v_mfma_f32_16x16x32_bf16 v[114:117], v[188:191], v[206:209], v[114:117]
	v_mfma_f32_16x16x32_bf16 v[106:109], v[180:183], v[214:217], v[106:109]
	v_mfma_f32_16x16x32_bf16 v[98:101], v[188:191], v[214:217], v[98:101]
	v_mfma_f32_16x16x32_bf16 v[90:93], v[180:183], v[222:225], v[90:93]
	v_mfma_f32_16x16x32_bf16 v[82:85], v[188:191], v[222:225], v[82:85]
	v_mfma_f32_16x16x32_bf16 v[74:77], v[180:183], v[230:233], v[74:77]
	v_mfma_f32_16x16x32_bf16 v[66:69], v[188:191], v[230:233], v[66:69]
	v_mfma_f32_16x16x32_bf16 v[122:125], v[184:187], v[210:213], v[122:125]
	v_mfma_f32_16x16x32_bf16 v[114:117], v[202:205], v[210:213], v[114:117]
	v_mfma_f32_16x16x32_bf16 v[106:109], v[184:187], v[218:221], v[106:109]
	v_mfma_f32_16x16x32_bf16 v[98:101], v[202:205], v[218:221], v[98:101]
	v_mfma_f32_16x16x32_bf16 v[90:93], v[184:187], v[226:229], v[90:93]
	v_mfma_f32_16x16x32_bf16 v[82:85], v[202:205], v[226:229], v[82:85]
	v_mfma_f32_16x16x32_bf16 v[74:77], v[184:187], v[234:237], v[74:77]
	v_mfma_f32_16x16x32_bf16 v[66:69], v[202:205], v[234:237], v[66:69]
	s_setprio 0
	s_barrier
; #define PG8_STAGE(bufoff, gbase, voff) do { _Pragma("unroll") for (int _i = 0; _i < 2; ++_i) \
;         __builtin_amdgcn_global_load_lds((const unsigned*)((const char*)(gbase) + (voff)[_i]), (PG8_LAS unsigned*)(lds + (bufoff) + ldsw + _i * 8192), 16, 0, 0); } while (0)
; #define PG8_LDA(dst, b, h) do { _Pragma("unroll") for (int m = 0; m < 4; ++m) _Pragma("unroll") for (int k = 0; k < 2; ++k) dst[m][k] = *(const PG8_LAS bf16x8*)(lds + PG8_SA(b, h) + aoff + m * 2048 + k * 1024); } while (0)
; #define PG8_MMA(ai, bj, At, Bt) do { __builtin_amdgcn_s_setprio(1); _Pragma("unroll") for (int m = 0; m < 4; ++m) _Pragma("unroll") for (int n = 0; n < 2; ++n) _Pragma("unroll") for (int k = 0; k < 2; ++k) \
;         acc[ai][bj][m][n] = __builtin_amdgcn_mfma_f32_16x16x32_bf16(Bt[n][k], At[m][k], acc[ai][bj][m][n], 0, 0, 0); __builtin_amdgcn_s_setprio(0); } while (0)
; #define PG8_WAIT_V(n) asm volatile("s_waitcnt vmcnt(" #n ")" ::: "memory")
; #define PG8_WAIT_L(n) asm volatile("s_waitcnt lgkmcnt(" #n ")" ::: "memory")
; #define PG8_BAR __builtin_amdgcn_s_barrier()
; #define PG8_SCHED __builtin_amdgcn_sched_barrier(0)
; #define PG8_STAGE(bufoff, gbase, voff) do { _Pragma("unroll") for (int _i = 0; _i < 2; ++_i) \
;         __builtin_amdgcn_global_load_lds((const unsigned*)((const char*)(gbase) + (voff)[_i]), (PG8_LAS unsigned*)(lds + (bufoff) + ldsw + _i * 8192), 16, 0, 0); } while (0)
; #define PG8_LDA(dst, b, h) do { _Pragma("unroll") for (int m = 0; m < 4; ++m) _Pragma("unroll") for (int k = 0; k < 2; ++k) dst[m][k] = *(const PG8_LAS bf16x8*)(lds + PG8_SA(b, h) + aoff + m * 2048 + k * 1024); } while (0)
; #define PG8_WAIT_V(n) asm volatile("s_waitcnt vmcnt(" #n ")" ::: "memory")
; #define PG8_WAIT_L(n) asm volatile("s_waitcnt lgkmcnt(" #n ")" ::: "memory")
; #define PG8_BAR __builtin_amdgcn_s_barrier()
; template <class Epi, class Sched, bool ALIGN_EPI = false, bool SP2 = false>
; __device__ __forceinline__ void gemm_phase(PG8_LAS unsigned char* lds, const Gemm g, const Sched& S, const Epi& E, const int tid_in) {
;     ...
;             PG8_LDA(At, 1, 1); PG8_STAGE(PG8_SB(1, 0), b3, voffB); PG8_STAGE(PG8_SB(1, 1), b3 + hstep, voffB); PG8_STAGE(PG8_SA(1, 0), a3, voffA);
;             PG8_WAIT_V(8); PG8_WAIT_L(0); PG8_BAR; PG8_MMA(1, 0, At, B0); PG8_MMA(1, 1, At, B1); PG8_BAR; PG8_SCHED;
;     ...
;         if constexpr (ALIGN_EPI) { if (wr == 0) PG8_BAR; }
	s_add_i32 s51, s51, s44
	v_lshl_add_u64 v[238:239], v[238:239], 0, s[82:83]
	s_mov_b32 m0, s51
	ds_read_b128 v[206:209], v159 offset:49152
	ds_read_b128 v[210:213], v159 offset:50176
	ds_read_b128 v[214:217], v159 offset:51200
	ds_read_b128 v[218:221], v159 offset:52224
	ds_read_b128 v[222:225], v159 offset:53248
	ds_read_b128 v[226:229], v159 offset:54272
	ds_read_b128 v[230:233], v159 offset:55296
	ds_read_b128 v[234:237], v159 offset:56320
	global_load_lds_dwordx4 v[238:239], off
	s_add_i32 m0, s51, 0x2000
	s_add_u32 s14, s14, 0x40080
	v_lshl_add_u64 v[238:239], v[240:241], 0, s[82:83]
	s_addc_u32 s15, s15, 0
	s_add_i32 s51, s68, s44
	global_load_lds_dwordx4 v[238:239], off
	v_lshl_add_u64 v[238:239], s[14:15], 0, v[132:133]
	s_mov_b32 m0, s51
	s_nop 0
	global_load_lds_dwordx4 v[238:239], off
	v_lshl_add_u64 v[238:239], s[14:15], 0, v[136:137]
	s_add_i32 m0, s51, 0x2000
	s_nop 0
	global_load_lds_dwordx4 v[238:239], off
	v_lshl_add_u64 v[238:239], v[242:243], 0, s[82:83]
	s_mov_b32 m0, s49
	s_nop 0
	global_load_lds_dwordx4 v[238:239], off
	v_lshl_add_u64 v[238:239], v[244:245], 0, s[82:83]
	s_mov_b32 m0, s94
	s_nop 0
	global_load_lds_dwordx4 v[238:239], off
	s_waitcnt vmcnt(8)
	s_waitcnt lgkmcnt(0)
	s_barrier
	s_setprio 1
	s_waitcnt lgkmcnt(0)
	v_mfma_f32_16x16x32_bf16 v[62:65], v[150:153], v[206:209], v[62:65]
	v_mfma_f32_16x16x32_bf16 v[54:57], v[172:175], v[206:209], v[54:57]
	v_mfma_f32_16x16x32_bf16 v[46:49], v[150:153], v[214:217], v[46:49]
	v_mfma_f32_16x16x32_bf16 v[38:41], v[172:175], v[214:217], v[38:41]
	v_mfma_f32_16x16x32_bf16 v[30:33], v[150:153], v[222:225], v[30:33]
	v_mfma_f32_16x16x32_bf16 v[22:25], v[172:175], v[222:225], v[22:25]
	v_mfma_f32_16x16x32_bf16 v[14:17], v[150:153], v[230:233], v[14:17]
	v_mfma_f32_16x16x32_bf16 v[6:9], v[172:175], v[230:233], v[6:9]
	v_mfma_f32_16x16x32_bf16 v[62:65], v[154:157], v[210:213], v[62:65]
	v_mfma_f32_16x16x32_bf16 v[54:57], v[176:179], v[210:213], v[54:57]
	v_mfma_f32_16x16x32_bf16 v[46:49], v[154:157], v[218:221], v[46:49]
	v_mfma_f32_16x16x32_bf16 v[38:41], v[176:179], v[218:221], v[38:41]
	v_mfma_f32_16x16x32_bf16 v[30:33], v[154:157], v[226:229], v[30:33]
	v_mfma_f32_16x16x32_bf16 v[22:25], v[176:179], v[226:229], v[22:25]
	v_mfma_f32_16x16x32_bf16 v[14:17], v[154:157], v[234:237], v[14:17]
	v_mfma_f32_16x16x32_bf16 v[6:9], v[176:179], v[234:237], v[6:9]
	s_setprio 0
	s_setprio 1
	v_mfma_f32_16x16x32_bf16 v[58:61], v[180:183], v[206:209], v[58:61]
	v_mfma_f32_16x16x32_bf16 v[50:53], v[188:191], v[206:209], v[50:53]
	v_mfma_f32_16x16x32_bf16 v[42:45], v[180:183], v[214:217], v[42:45]
	v_mfma_f32_16x16x32_bf16 v[34:37], v[188:191], v[214:217], v[34:37]
	v_mfma_f32_16x16x32_bf16 v[26:29], v[180:183], v[222:225], v[26:29]
	v_mfma_f32_16x16x32_bf16 v[18:21], v[188:191], v[222:225], v[18:21]
	v_mfma_f32_16x16x32_bf16 v[10:13], v[180:183], v[230:233], v[10:13]
	v_mfma_f32_16x16x32_bf16 v[2:5], v[188:191], v[230:233], v[2:5]
	v_mfma_f32_16x16x32_bf16 v[58:61], v[184:187], v[210:213], v[58:61]
	v_mfma_f32_16x16x32_bf16 v[50:53], v[202:205], v[210:213], v[50:53]
	v_mfma_f32_16x16x32_bf16 v[42:45], v[184:187], v[218:221], v[42:45]
	v_mfma_f32_16x16x32_bf16 v[34:37], v[202:205], v[218:221], v[34:37]
	v_mfma_f32_16x16x32_bf16 v[26:29], v[184:187], v[226:229], v[26:29]
	v_mfma_f32_16x16x32_bf16 v[18:21], v[202:205], v[226:229], v[18:21]
	v_mfma_f32_16x16x32_bf16 v[10:13], v[184:187], v[234:237], v[10:13]
	v_mfma_f32_16x16x32_bf16 v[2:5], v[202:205], v[234:237], v[2:5]
	s_add_i32 vcc_hi, vcc_hi, 2
	s_add_u32 s8, s8, 0x100
	s_addc_u32 s9, s9, 0
	s_add_u32 s91, s91, 0x100
	s_addc_u32 vcc_lo, vcc_lo, 0
	s_cmp_gt_u32 vcc_hi, 13
	s_setprio 0
	s_barrier
	s_cbranch_scc0 .LBB0_221
	s_and_b64 vcc, exec, s[72:73]
	s_cbranch_vccz .LBB0_224
	s_barrier
